# MoBA block choice: the eight k-sum loads of each conditional key-block section issued together (hipcc had four dependent pairs per section)
# baseline (speedup 1.0000x reference)
; #define DMA_K(t, slot) glds16(ksrc + (long)(t) * KVBLK * KP, (unsigned)__builtin_amdgcn_readfirstlane(kdst + (slot)))
; #define DMA_V(t, slot) glds16(vsrc + (long)(t) * KVBLK * KP, (unsigned)__builtin_amdgcn_readfirstlane(vdst + (slot)))
; __device__ __forceinline__ unsigned moba_select(int b, int h, int qb, const f16_t* Q, const float* __restrict__ kms) {
;     int tid_ = threadIdx.x; asm volatile("" : "+v"(tid_));
;     const int tid = tid_, lane = tid & 63, r32 = lane & 31, hi = lane >> 5; const int wid = __builtin_amdgcn_readfirstlane(tid >> 6);
;     const f16_t* Qw = Q + ((long)b * SEQ + qb * QB + wid * QBLK) * QP + h * HD;
;     f16x8 qr[4];
; #pragma unroll
;     for (int d0 = 0; d0 < 4; ++d0) qr[d0] = *reinterpret_cast<const f16x8*>(&Qw[(long)r32 * QP + d0 * 16 + hi * 8]);
;     float gsc[7];
; #pragma unroll
;     for (int j = 0; j < 7; ++j) {
;         float s = 0.f;
;         if (j < qb) {
;             const float* km = kms + (size_t)(b * NBLK + j) * AW + h * HD + hi * 8;
; #pragma unroll
;             for (int d0 = 0; d0 < 4; ++d0) {
;                 const f32x4 k0 = *(const f32x4*)(km + d0 * 16), k1 = *(const f32x4*)(km + d0 * 16 + 4);
;                 s += (float)qr[d0][0] * k0[0] + (float)qr[d0][1] * k0[1] + (float)qr[d0][2] * k0[2] + (float)qr[d0][3] * k0[3];
;                 s += (float)qr[d0][4] * k1[0] + (float)qr[d0][5] * k1[1] + (float)qr[d0][6] * k1[2] + (float)qr[d0][7] * k1[3];
;             }
; template <int THRL> __device__ __forceinline__ void attn_unit(int b, int h, int qb, const f16_t* Q, const f16_t* __restrict__ K, const f16_t* __restrict__ V, f16_t* O, const float* __restrict__ kms, char* shm) {
;     ...
;     const f16_t* ksrc = Kh + (long)lane * KP + wid * 8;
;     const f16_t* vsrc = Vh + (long)(16 * (wid & 3) + (lane >> 2)) * KP + (wid >> 2) * 32 + (lane & 3) * 8;
;     const unsigned kdst = lds0 + LDS_K + wid * 1024, vdst = lds0 + LDS_V + wid * 1024;
;     ...
;     const int vb0 = (int)(lds0 + LDS_V) + ((lane >> 4) & 1) * 32 + (lane & 3) * 8 + (4 * hi + ((lane & 15) >> 2)) * 64;
;     const char* Kbase = shm + LDS_K; f16x8 kf[8];
;     const lds_cptr shm3 = (lds_cptr)shm; const lds_cptr kp0 = shm3 + LDS_K + hi * 1024 + r32 * 16; const lds_cptr vp0 = shm3 + LDS_V + ((lane >> 4) & 1) * 32 + (lane & 3) * 8 + (4 * hi + ((lane & 15) >> 2)) * 64;
;     const int NT = (q0 + QB) / KVBLK;
;     DMA_K(0, 0); DMA_V(0, 0); DMA_K(1, SLOTB);
.LBB0_530:
	v_mov_b32_e32 v150, v0
	s_and_b64 s[0:1], s[2:3], exec
	s_cselect_b32 s70, s7, s78
	v_readfirstlane_b32 s24, v150
	v_and_b32_e32 v201, 63, v150
	s_ashr_i32 s29, s24, 6
	v_lshlrev_b32_e32 v190, 10, v201
	s_lshl_b32 s0, s29, 3
	v_lshl_add_u64 v[2:3], s[58:59], 0, v[190:191]
	s_ashr_i32 s1, s0, 31
	v_lshl_add_u64 v[182:183], s[0:1], 1, v[2:3]
	s_lshl_b32 s0, s29, 4
	v_bfe_u32 v2, v150, 2, 4
	v_and_or_b32 v2, s0, 48, v2
	s_ashr_i32 s0, s24, 3
	s_lshl_b32 s71, s70, 8
	s_andn2_b32 s0, s0, 31
	s_or_b32 s8, s56, s71
	v_lshlrev_b32_e32 v190, 10, v2
	s_ashr_i32 s1, s0, 31
	s_lshl_b32 s11, s29, 10
	v_lshl_add_u64 v[2:3], s[60:61], 0, v[190:191]
	v_lshlrev_b32_e32 v202, 3, v150
	s_cmp_lg_u32 0, -1
	v_lshl_add_u64 v[2:3], s[0:1], 1, v[2:3]
	v_and_b32_e32 v203, 24, v202
	s_cselect_b32 s0, 0, 0
	v_lshlrev_b32_e32 v190, 1, v203
	s_add_i32 s76, s11, s0
	s_mov_b32 s0, m0
	s_mov_b32 m0, s76
	s_nop 0
	global_load_lds_dwordx4 v[182:183], off
	s_mov_b32 m0, s0
	v_lshl_add_u64 v[104:105], v[2:3], 0, v[190:191]
	s_add_i32 s77, s76, 0x6000
	s_mov_b32 s0, m0
	s_mov_b32 m0, s77
	s_nop 0
	global_load_lds_dwordx4 v[104:105], off
	s_mov_b32 m0, s0
	v_lshl_add_u64 v[2:3], v[182:183], 0, s[42:43]
	s_add_i32 s0, s76, 0x2000
	s_mov_b32 s1, m0
	s_mov_b32 m0, s0
	s_nop 0
	global_load_lds_dwordx4 v[2:3], off
	s_mov_b32 m0, s1
	s_cmp_gt_u32 s70, 3
	s_cselect_b64 s[4:5], -1, 0
	s_cmp_lt_u32 s70, 4
	v_mov_b32_e32 v210, -1
	s_cbranch_scc1 .LBB0_538
	v_mov_b32_e32 v2, v0
	s_movk_i32 s9, 0x7c00
	v_readfirstlane_b32 s0, v2
	s_ashr_i32 s0, s0, 1
	s_andn2_b32 s0, s0, 31
	s_ashr_i32 s1, s0, 31
	s_add_u32 s0, s8, s0
	s_addc_u32 s1, s57, s1
	v_lshlrev_b32_e32 v3, 10, v2
	v_lshrrev_b32_e32 v2, 2, v2
	s_lshl_b64 s[0:1], s[0:1], 11
	v_and_b32_e32 v10, 8, v2
	s_add_u32 s0, s79, s0
	v_and_or_b32 v2, v3, s9, v10
	s_addc_u32 s1, s14, s1
	v_lshlrev_b32_e32 v11, 1, v2
	global_load_dwordx4 v[2:5], v11, s[0:1]
	global_load_dwordx4 v[6:9], v11, s[0:1] offset:32
	global_load_dwordx4 v[30:33], v11, s[0:1] offset:64
	global_load_dwordx4 v[34:37], v11, s[0:1] offset:96
	v_lshlrev_b32_e32 v190, 2, v10
	s_waitcnt lgkmcnt(14)
	v_lshl_add_u64 v[132:133], s[62:63], 0, v[190:191]
	v_lshl_add_u64 v[38:39], v[132:133], 0, s[64:65]
	v_lshl_add_u64 v[50:51], v[132:133], 0, s[66:67]
	global_load_dwordx4 v[26:29], v[38:39], off offset:16
	global_load_dwordx4 v[42:45], v[38:39], off
	global_load_dwordx4 v[18:21], v[38:39], off offset:80
	global_load_dwordx4 v[22:25], v[38:39], off offset:64
	global_load_dwordx4 v[10:13], v[38:39], off offset:144
	global_load_dwordx4 v[14:17], v[38:39], off offset:128
	v_cmp_lt_i32_e32 vcc, v197, v198
	v_lshl_add_u64 v[58:59], v[132:133], 0, s[90:91]
	s_waitcnt lgkmcnt(7)
	v_lshl_add_u64 v[146:147], v[132:133], 0, s[92:93]
	s_cmp_lg_u32 s70, 4
	s_cselect_b64 s[0:1], -1, 0
	s_cmp_eq_u32 s70, 4
	s_waitcnt vmcnt(9)
	v_cvt_f32_f16_e32 v131, v4
	v_cvt_f32_f16_e32 v130, v2
	v_cvt_f32_f16_sdwa v139, v4 dst_sel:DWORD dst_unused:UNUSED_PAD src0_sel:WORD_1
	v_cvt_f32_f16_sdwa v138, v2 dst_sel:DWORD dst_unused:UNUSED_PAD src0_sel:WORD_1
	v_cvt_f32_f16_e32 v135, v5
	v_cvt_f32_f16_e32 v134, v3
	v_cvt_f32_f16_sdwa v137, v5 dst_sel:DWORD dst_unused:UNUSED_PAD src0_sel:WORD_1
	v_cvt_f32_f16_sdwa v136, v3 dst_sel:DWORD dst_unused:UNUSED_PAD src0_sel:WORD_1
	s_waitcnt vmcnt(8)
	v_cvt_f32_f16_e32 v123, v8
	v_cvt_f32_f16_e32 v122, v6
	v_cvt_f32_f16_sdwa v129, v8 dst_sel:DWORD dst_unused:UNUSED_PAD src0_sel:WORD_1
	v_cvt_f32_f16_sdwa v128, v6 dst_sel:DWORD dst_unused:UNUSED_PAD src0_sel:WORD_1
	v_cvt_f32_f16_e32 v125, v9
	v_cvt_f32_f16_e32 v124, v7
	v_cvt_f32_f16_sdwa v127, v9 dst_sel:DWORD dst_unused:UNUSED_PAD src0_sel:WORD_1
	v_cvt_f32_f16_sdwa v126, v7 dst_sel:DWORD dst_unused:UNUSED_PAD src0_sel:WORD_1
	s_waitcnt vmcnt(7)
	v_cvt_f32_f16_e32 v115, v32
	v_cvt_f32_f16_sdwa v121, v32 dst_sel:DWORD dst_unused:UNUSED_PAD src0_sel:WORD_1
	v_cvt_f32_f16_e32 v117, v33
	v_cvt_f32_f16_sdwa v119, v33 dst_sel:DWORD dst_unused:UNUSED_PAD src0_sel:WORD_1
	global_load_dwordx4 v[2:5], v[38:39], off offset:208
	global_load_dwordx4 v[6:9], v[38:39], off offset:192
	s_waitcnt vmcnt(8)
	v_cvt_f32_f16_e32 v110, v34
	v_cvt_f32_f16_sdwa v112, v34 dst_sel:DWORD dst_unused:UNUSED_PAD src0_sel:WORD_1
	v_cvt_f32_f16_e32 v108, v35
	v_cvt_f32_f16_sdwa v106, v35 dst_sel:DWORD dst_unused:UNUSED_PAD src0_sel:WORD_1
	global_load_dwordx4 v[32:35], v[50:51], off offset:16
	global_load_dwordx4 v[38:41], v[50:51], off
	v_cvt_f32_f16_e32 v114, v30
	v_cvt_f32_f16_sdwa v120, v30 dst_sel:DWORD dst_unused:UNUSED_PAD src0_sel:WORD_1
	v_cvt_f32_f16_e32 v116, v31
	v_cvt_f32_f16_sdwa v118, v31 dst_sel:DWORD dst_unused:UNUSED_PAD src0_sel:WORD_1
	v_cndmask_b32_e32 v30, v196, v197, vcc
	v_cvt_f32_f16_e32 v111, v36
	v_cvt_f32_f16_sdwa v113, v36 dst_sel:DWORD dst_unused:UNUSED_PAD src0_sel:WORD_1
	v_cvt_f32_f16_e32 v109, v37
	v_cvt_f32_f16_sdwa v107, v37 dst_sel:DWORD dst_unused:UNUSED_PAD src0_sel:WORD_1
	v_lshlrev_b32_e32 v151, 2, v30
	s_waitcnt vmcnt(8)
	v_mov_b32_e32 v30, v42
	v_mov_b32_e32 v94, v139
	v_mov_b32_e32 v92, v131
	s_waitcnt vmcnt(6)
	v_mov_b32_e32 v144, v22
	v_mov_b32_e32 v142, v28
	v_mov_b32_e32 v28, v135
	s_waitcnt vmcnt(1)
	v_mov_b32_e32 v143, v34
	s_waitcnt vmcnt(0)
; __device__ __forceinline__ unsigned moba_select(int b, int h, int qb, const f16_t* Q, const float* __restrict__ kms) {
;     ...
;     for (int j = 0; j < 7; ++j) {
;         float s = 0.f;
;         if (j < qb) {
;             const float* km = kms + (size_t)(b * NBLK + j) * AW + h * HD + hi * 8;
; #pragma unroll
;             for (int d0 = 0; d0 < 4; ++d0) {
;                 const f32x4 k0 = *(const f32x4*)(km + d0 * 16), k1 = *(const f32x4*)(km + d0 * 16 + 4);
;                 s += (float)qr[d0][0] * k0[0] + (float)qr[d0][1] * k0[1] + (float)qr[d0][2] * k0[2] + (float)qr[d0][3] * k0[3];
;                 s += (float)qr[d0][4] * k1[0] + (float)qr[d0][5] * k1[1] + (float)qr[d0][6] * k1[2] + (float)qr[d0][7] * k1[3];
;             }
;             s += __shfl_xor(s, 32);
	v_mov_b32_e32 v31, v38
	v_mov_b32_e32 v38, v43
	v_pk_mul_f32 v[36:37], v[38:39], v[138:139] op_sel_hi:[1,0]
	v_mov_b32_e32 v34, v29
	v_pk_fma_f32 v[30:31], v[30:31], v[130:131], v[36:37] op_sel_hi:[1,0,1]
	v_mov_b32_e32 v36, v44
	v_mov_b32_e32 v37, v40
	v_pk_fma_f32 v[140:141], v[36:37], v[134:135], v[30:31] op_sel_hi:[1,0,1]
	v_mov_b32_e32 v31, v32
	v_mov_b32_e32 v32, v27
	v_mov_b32_e32 v30, v26
	v_pk_mul_f32 v[26:27], v[32:33], v[94:95] op_sel_hi:[1,0]
	v_mov_b32_e32 v40, v45
	v_pk_fma_f32 v[26:27], v[30:31], v[92:93], v[26:27] op_sel_hi:[1,0,1]
	global_load_dwordx4 v[30:33], v[50:51], off offset:80
	global_load_dwordx4 v[64:67], v[50:51], off offset:64
	global_load_dwordx4 v[46:49], v[50:51], off offset:144
	global_load_dwordx4 v[54:57], v[50:51], off offset:128
	global_load_dwordx4 v[36:39], v[50:51], off offset:208
	global_load_dwordx4 v[42:45], v[50:51], off offset:192
	v_pk_fma_f32 v[40:41], v[40:41], v[136:137], v[140:141] op_sel_hi:[1,0,1]
	v_pk_fma_f32 v[26:27], v[142:143], v[28:29], v[26:27] op_sel_hi:[1,0,1]
	v_pk_add_f32 v[40:41], v[40:41], 0 op_sel_hi:[1,0]
	s_waitcnt vmcnt(4)
	v_mov_b32_e32 v145, v64
	v_mov_b32_e32 v64, v23
	v_pk_mul_f32 v[22:23], v[64:65], v[128:129] op_sel_hi:[1,0]
	global_load_dwordx4 v[80:83], v[58:59], off offset:16
	global_load_dwordx4 v[96:99], v[58:59], off
	global_load_dwordx4 v[72:75], v[58:59], off offset:80
	global_load_dwordx4 v[76:79], v[58:59], off offset:64
	global_load_dwordx4 v[62:65], v[58:59], off offset:144
	global_load_dwordx4 v[68:71], v[58:59], off offset:128
	global_load_dwordx4 v[50:53], v[58:59], off offset:208
	s_nop 0
	global_load_dwordx4 v[58:61], v[58:59], off offset:192
	s_nop 0
	global_load_dwordx4 v[84:87], v[146:147], off offset:16
	global_load_dwordx4 v[88:91], v[146:147], off
	v_pk_fma_f32 v[22:23], v[144:145], v[122:123], v[22:23] op_sel_hi:[1,0,1]
	s_waitcnt vmcnt(8)
	v_mov_b32_e32 v100, v96
	v_mov_b32_e32 v96, v98
	s_waitcnt vmcnt(6)
	v_mov_b32_e32 v148, v76
	s_waitcnt vmcnt(0)
	v_mov_b32_e32 v101, v88
	v_mov_b32_e32 v88, v97
	v_pk_mul_f32 v[88:89], v[88:89], v[138:139] op_sel_hi:[1,0]
	v_mov_b32_e32 v97, v90
	v_pk_fma_f32 v[88:89], v[100:101], v[130:131], v[88:89] op_sel_hi:[1,0,1]
	v_mov_b32_e32 v90, v99
	v_pk_fma_f32 v[88:89], v[96:97], v[134:135], v[88:89] op_sel_hi:[1,0,1]
	v_mov_b32_e32 v97, v84
	v_mov_b32_e32 v84, v81
	v_mov_b32_e32 v96, v80
	v_pk_mul_f32 v[80:81], v[84:85], v[94:95] op_sel_hi:[1,0]
	v_mov_b32_e32 v84, v82
	v_pk_fma_f32 v[80:81], v[96:97], v[92:93], v[80:81] op_sel_hi:[1,0,1]
	global_load_dwordx4 v[92:95], v[146:147], off offset:80
	global_load_dwordx4 v[96:99], v[146:147], off offset:64
	global_load_dwordx4 v[100:103], v[146:147], off offset:144
	s_waitcnt lgkmcnt(2)
	global_load_dwordx4 v[152:155], v[146:147], off offset:128
	s_waitcnt lgkmcnt(1)
	global_load_dwordx4 v[156:159], v[146:147], off offset:208
	s_waitcnt lgkmcnt(0)
	global_load_dwordx4 v[160:163], v[146:147], off offset:192
	v_mov_b32_e32 v85, v86
	v_pk_fma_f32 v[80:81], v[84:85], v[28:29], v[80:81] op_sel_hi:[1,0,1]
	v_mov_b32_e32 v28, v137
	v_pk_fma_f32 v[26:27], v[34:35], v[28:29], v[26:27] op_sel_hi:[1,0,1]
	v_pk_fma_f32 v[88:89], v[90:91], v[136:137], v[88:89] op_sel_hi:[1,0,1]
	v_pk_add_f32 v[26:27], v[40:41], v[26:27]
	v_mov_b32_e32 v40, v24
	v_mov_b32_e32 v41, v66
	v_mov_b32_e32 v86, v83
	v_pk_fma_f32 v[22:23], v[40:41], v[124:125], v[22:23] op_sel_hi:[1,0,1]
	v_mov_b32_e32 v40, v78
	v_pk_add_f32 v[88:89], v[88:89], 0 op_sel_hi:[1,0]
	v_pk_fma_f32 v[28:29], v[86:87], v[28:29], v[80:81] op_sel_hi:[1,0,1]
	v_mov_b32_e32 v66, v25
	v_pk_add_f32 v[28:29], v[88:89], v[28:29]
	v_pk_fma_f32 v[22:23], v[66:67], v[126:127], v[22:23] op_sel_hi:[1,0,1]
	s_waitcnt vmcnt(4)
	v_mov_b32_e32 v149, v96
	v_mov_b32_e32 v96, v77
	v_pk_mul_f32 v[76:77], v[96:97], v[128:129] op_sel_hi:[1,0]
	v_mov_b32_e32 v41, v98
	v_pk_fma_f32 v[34:35], v[148:149], v[122:123], v[76:77] op_sel_hi:[1,0,1]
	v_mov_b32_e32 v98, v79
	v_pk_fma_f32 v[34:35], v[40:41], v[124:125], v[34:35] op_sel_hi:[1,0,1]
	v_pk_add_f32 v[22:23], v[26:27], v[22:23]
	v_pk_fma_f32 v[34:35], v[98:99], v[126:127], v[34:35] op_sel_hi:[1,0,1]
	v_mov_b32_e32 v26, v129
	v_pk_add_f32 v[24:25], v[28:29], v[34:35]
	v_mov_b32_e32 v28, v73
	v_mov_b32_e32 v29, v93
	v_mov_b32_e32 v34, v19
	v_mov_b32_e32 v35, v31
	v_pk_mul_f32 v[28:29], v[28:29], v[26:27] op_sel_hi:[1,0]
	v_pk_mul_f32 v[26:27], v[34:35], v[26:27] op_sel_hi:[1,0]
	v_mov_b32_e32 v34, v123
	v_mov_b32_e32 v19, v30
	v_mov_b32_e32 v73, v92
	v_pk_fma_f32 v[18:19], v[18:19], v[34:35], v[26:27] op_sel_hi:[1,0,1]
	v_pk_fma_f32 v[26:27], v[72:73], v[34:35], v[28:29] op_sel_hi:[1,0,1]
	v_mov_b32_e32 v28, v125
	v_mov_b32_e32 v30, v74
	v_mov_b32_e32 v31, v94
	v_pk_fma_f32 v[26:27], v[30:31], v[28:29], v[26:27] op_sel_hi:[1,0,1]
	v_mov_b32_e32 v30, v20
	v_mov_b32_e32 v31, v32
	v_pk_fma_f32 v[18:19], v[30:31], v[28:29], v[18:19] op_sel_hi:[1,0,1]
	v_mov_b32_e32 v20, v127
	v_mov_b32_e32 v32, v21
	v_pk_fma_f32 v[18:19], v[32:33], v[20:21], v[18:19] op_sel_hi:[1,0,1]
	v_mov_b32_e32 v94, v75
	v_pk_fma_f32 v[20:21], v[94:95], v[20:21], v[26:27] op_sel_hi:[1,0,1]
	v_pk_add_f32 v[18:19], v[22:23], v[18:19]
	v_mov_b32_e32 v22, v15
	v_mov_b32_e32 v23, v55
	v_pk_add_f32 v[20:21], v[24:25], v[20:21]
	v_pk_mul_f32 v[22:23], v[22:23], v[120:121] op_sel_hi:[1,0]
	v_mov_b32_e32 v24, v69
	s_waitcnt vmcnt(2)
; __device__ __forceinline__ unsigned moba_select(int b, int h, int qb, const f16_t* Q, const float* __restrict__ kms) {
;     ...
;     for (int j = 0; j < 7; ++j) {
;         float s = 0.f;
;         if (j < qb) {
;             const float* km = kms + (size_t)(b * NBLK + j) * AW + h * HD + hi * 8;
; #pragma unroll
;             for (int d0 = 0; d0 < 4; ++d0) {
;                 const f32x4 k0 = *(const f32x4*)(km + d0 * 16), k1 = *(const f32x4*)(km + d0 * 16 + 4);
;                 s += (float)qr[d0][0] * k0[0] + (float)qr[d0][1] * k0[1] + (float)qr[d0][2] * k0[2] + (float)qr[d0][3] * k0[3];
;                 s += (float)qr[d0][4] * k1[0] + (float)qr[d0][5] * k1[1] + (float)qr[d0][6] * k1[2] + (float)qr[d0][7] * k1[3];
;             }
;             s += __shfl_xor(s, 32);
;         } else s = -INFINITY;
;         gsc[j] = s;
	v_mov_b32_e32 v25, v153
	v_mov_b32_e32 v15, v54
	v_pk_mul_f32 v[24:25], v[24:25], v[120:121] op_sel_hi:[1,0]
	v_mov_b32_e32 v69, v152
	v_pk_fma_f32 v[14:15], v[14:15], v[114:115], v[22:23] op_sel_hi:[1,0,1]
	v_mov_b32_e32 v22, v16
	v_mov_b32_e32 v23, v56
	v_pk_fma_f32 v[24:25], v[68:69], v[114:115], v[24:25] op_sel_hi:[1,0,1]
	v_pk_fma_f32 v[14:15], v[22:23], v[116:117], v[14:15] op_sel_hi:[1,0,1]
	v_mov_b32_e32 v22, v70
	v_mov_b32_e32 v23, v154
	v_pk_fma_f32 v[22:23], v[22:23], v[116:117], v[24:25] op_sel_hi:[1,0,1]
	v_mov_b32_e32 v154, v71
	v_mov_b32_e32 v56, v17
	v_pk_fma_f32 v[22:23], v[154:155], v[118:119], v[22:23] op_sel_hi:[1,0,1]
	v_pk_fma_f32 v[14:15], v[56:57], v[118:119], v[14:15] op_sel_hi:[1,0,1]
	v_pk_add_f32 v[16:17], v[20:21], v[22:23]
	v_pk_add_f32 v[14:15], v[18:19], v[14:15]
	v_mov_b32_e32 v18, v121
	v_mov_b32_e32 v20, v63
	v_mov_b32_e32 v21, v101
	v_mov_b32_e32 v22, v11
	v_mov_b32_e32 v23, v47
	v_pk_mul_f32 v[20:21], v[20:21], v[18:19] op_sel_hi:[1,0]
	v_pk_mul_f32 v[18:19], v[22:23], v[18:19] op_sel_hi:[1,0]
	v_mov_b32_e32 v22, v115
	v_mov_b32_e32 v11, v46
	v_mov_b32_e32 v63, v100
	v_pk_fma_f32 v[10:11], v[10:11], v[22:23], v[18:19] op_sel_hi:[1,0,1]
	v_pk_fma_f32 v[18:19], v[62:63], v[22:23], v[20:21] op_sel_hi:[1,0,1]
	v_mov_b32_e32 v20, v117
	v_mov_b32_e32 v22, v64
	v_mov_b32_e32 v23, v102
	v_pk_fma_f32 v[18:19], v[22:23], v[20:21], v[18:19] op_sel_hi:[1,0,1]
	v_mov_b32_e32 v22, v12
	v_mov_b32_e32 v23, v48
	v_pk_fma_f32 v[10:11], v[22:23], v[20:21], v[10:11] op_sel_hi:[1,0,1]
	v_mov_b32_e32 v12, v119
	v_mov_b32_e32 v48, v13
	v_pk_fma_f32 v[10:11], v[48:49], v[12:13], v[10:11] op_sel_hi:[1,0,1]
	v_mov_b32_e32 v102, v65
	v_pk_fma_f32 v[12:13], v[102:103], v[12:13], v[18:19] op_sel_hi:[1,0,1]
	v_pk_add_f32 v[10:11], v[14:15], v[10:11]
	v_mov_b32_e32 v14, v7
	v_mov_b32_e32 v15, v43
	v_pk_add_f32 v[12:13], v[16:17], v[12:13]
	v_pk_mul_f32 v[14:15], v[14:15], v[112:113] op_sel_hi:[1,0]
	v_mov_b32_e32 v16, v59
	s_waitcnt vmcnt(0)
	v_mov_b32_e32 v17, v161
	v_mov_b32_e32 v7, v42
	v_pk_mul_f32 v[16:17], v[16:17], v[112:113] op_sel_hi:[1,0]
	v_mov_b32_e32 v59, v160
	v_pk_fma_f32 v[6:7], v[6:7], v[110:111], v[14:15] op_sel_hi:[1,0,1]
	v_mov_b32_e32 v14, v8
	v_mov_b32_e32 v15, v44
	v_pk_fma_f32 v[16:17], v[58:59], v[110:111], v[16:17] op_sel_hi:[1,0,1]
	v_pk_fma_f32 v[6:7], v[14:15], v[108:109], v[6:7] op_sel_hi:[1,0,1]
	v_mov_b32_e32 v14, v60
	v_mov_b32_e32 v15, v162
	v_pk_fma_f32 v[14:15], v[14:15], v[108:109], v[16:17] op_sel_hi:[1,0,1]
	v_mov_b32_e32 v162, v61
	v_mov_b32_e32 v44, v9
	v_pk_fma_f32 v[14:15], v[162:163], v[106:107], v[14:15] op_sel_hi:[1,0,1]
	v_pk_fma_f32 v[6:7], v[44:45], v[106:107], v[6:7] op_sel_hi:[1,0,1]
	s_nop 0
	v_pk_add_f32 v[8:9], v[10:11], v[6:7]
	v_pk_add_f32 v[6:7], v[12:13], v[14:15]
	v_mov_b32_e32 v10, v113
	v_mov_b32_e32 v12, v51
	v_mov_b32_e32 v13, v157
	v_mov_b32_e32 v14, v3
	v_mov_b32_e32 v15, v37
	v_pk_mul_f32 v[12:13], v[12:13], v[10:11] op_sel_hi:[1,0]
	v_pk_mul_f32 v[10:11], v[14:15], v[10:11] op_sel_hi:[1,0]
	v_mov_b32_e32 v14, v111
	v_mov_b32_e32 v3, v36
	v_mov_b32_e32 v51, v156
	v_pk_fma_f32 v[2:3], v[2:3], v[14:15], v[10:11] op_sel_hi:[1,0,1]
	v_pk_fma_f32 v[10:11], v[50:51], v[14:15], v[12:13] op_sel_hi:[1,0,1]
	v_mov_b32_e32 v12, v109
	v_mov_b32_e32 v14, v52
	v_mov_b32_e32 v15, v158
	v_pk_fma_f32 v[10:11], v[14:15], v[12:13], v[10:11] op_sel_hi:[1,0,1]
	v_mov_b32_e32 v14, v4
	v_mov_b32_e32 v15, v38
	v_pk_fma_f32 v[2:3], v[14:15], v[12:13], v[2:3] op_sel_hi:[1,0,1]
	v_mov_b32_e32 v4, v107
	v_mov_b32_e32 v38, v5
	v_mov_b32_e32 v158, v53
	v_pk_fma_f32 v[2:3], v[38:39], v[4:5], v[2:3] op_sel_hi:[1,0,1]
	v_pk_fma_f32 v[4:5], v[158:159], v[4:5], v[10:11] op_sel_hi:[1,0,1]
	v_pk_add_f32 v[2:3], v[8:9], v[2:3]
	v_pk_add_f32 v[6:7], v[6:7], v[4:5]
	ds_bpermute_b32 v4, v151, v2
	ds_bpermute_b32 v5, v151, v3
	ds_bpermute_b32 v8, v151, v6
	ds_bpermute_b32 v9, v151, v7
	v_mov_b32_e32 v10, 0xff800000
	v_mov_b32_e32 v11, 0xff800000
	s_cbranch_scc1 .LBB0_533
	v_lshl_add_u64 v[20:21], v[132:133], 0, s[94:95]
	global_load_dwordx4 v[12:15], v[20:21], off
	global_load_dwordx4 v[16:19], v[20:21], off offset:16
	global_load_dwordx4 v[218:221], v[20:21], off offset:64
	global_load_dwordx4 v[222:225], v[20:21], off offset:80
	global_load_dwordx4 v[232:235], v[20:21], off offset:128
	global_load_dwordx4 v[236:239], v[20:21], off offset:144
	global_load_dwordx4 v[240:243], v[20:21], off offset:192
	global_load_dwordx4 v[244:247], v[20:21], off offset:208
	s_waitcnt vmcnt(7)
	v_mov_b32_e32 v22, v12
	s_waitcnt vmcnt(6)
	v_mov_b32_e32 v23, v16
	v_mov_b32_e32 v16, v13
	v_pk_mul_f32 v[12:13], v[16:17], v[138:139]
	v_mov_b32_e32 v16, v14
	v_pk_fma_f32 v[12:13], v[22:23], v[130:131], v[12:13]
	v_mov_b32_e32 v17, v18
	v_pk_fma_f32 v[12:13], v[16:17], v[134:135], v[12:13]
	v_mov_b32_e32 v18, v15
	v_pk_fma_f32 v[12:13], v[18:19], v[136:137], v[12:13]
	s_nop 0
	v_add_f32_e32 v11, 0, v12
	v_add_f32_e32 v11, v11, v13
	s_waitcnt vmcnt(4)
	v_mov_b32_e32 v12, v218
	v_mov_b32_e32 v13, v219
	v_mov_b32_e32 v14, v220
	v_mov_b32_e32 v15, v221
	v_mov_b32_e32 v16, v222
	v_mov_b32_e32 v17, v223
	v_mov_b32_e32 v18, v224
	v_mov_b32_e32 v19, v225
	v_mov_b32_e32 v22, v12
	v_mov_b32_e32 v23, v16
	v_mov_b32_e32 v16, v13
	v_pk_mul_f32 v[12:13], v[16:17], v[128:129]
	v_mov_b32_e32 v16, v14
	v_pk_fma_f32 v[12:13], v[22:23], v[122:123], v[12:13]
	v_mov_b32_e32 v17, v18
	v_pk_fma_f32 v[12:13], v[16:17], v[124:125], v[12:13]
	v_mov_b32_e32 v18, v15
	v_pk_fma_f32 v[12:13], v[18:19], v[126:127], v[12:13]
	s_nop 0
	v_add_f32_e32 v11, v11, v12
	v_add_f32_e32 v11, v11, v13
	s_waitcnt vmcnt(2)
	v_mov_b32_e32 v12, v232
	v_mov_b32_e32 v13, v233
	v_mov_b32_e32 v14, v234
	v_mov_b32_e32 v15, v235
	v_mov_b32_e32 v16, v236
	v_mov_b32_e32 v17, v237
	v_mov_b32_e32 v18, v238
	v_mov_b32_e32 v19, v239
	v_mov_b32_e32 v22, v12
	v_mov_b32_e32 v23, v16
	v_mov_b32_e32 v16, v13
	v_pk_mul_f32 v[12:13], v[16:17], v[120:121]
	v_mov_b32_e32 v16, v14
	v_pk_fma_f32 v[12:13], v[22:23], v[114:115], v[12:13]
	v_mov_b32_e32 v17, v18
	v_pk_fma_f32 v[12:13], v[16:17], v[116:117], v[12:13]
	v_mov_b32_e32 v18, v15
	v_pk_fma_f32 v[12:13], v[18:19], v[118:119], v[12:13]
	s_nop 0
	v_add_f32_e32 v11, v11, v12
	v_add_f32_e32 v11, v11, v13
	s_waitcnt vmcnt(0)
	v_mov_b32_e32 v12, v240
	v_mov_b32_e32 v13, v241
	v_mov_b32_e32 v14, v242
	v_mov_b32_e32 v15, v243
	v_mov_b32_e32 v16, v244
	v_mov_b32_e32 v17, v245
	v_mov_b32_e32 v18, v246
	v_mov_b32_e32 v19, v247
	v_mov_b32_e32 v20, v12
	v_mov_b32_e32 v21, v16
	v_mov_b32_e32 v16, v13
	v_pk_mul_f32 v[12:13], v[16:17], v[112:113]
	v_mov_b32_e32 v16, v14
	v_pk_fma_f32 v[12:13], v[20:21], v[110:111], v[12:13]
	v_mov_b32_e32 v17, v18
	v_pk_fma_f32 v[12:13], v[16:17], v[108:109], v[12:13]
	v_mov_b32_e32 v18, v15
	v_pk_fma_f32 v[12:13], v[18:19], v[106:107], v[12:13]
	s_nop 0
	v_add_f32_e32 v11, v11, v12
	v_add_f32_e32 v11, v11, v13
	ds_bpermute_b32 v12, v151, v11
	s_waitcnt lgkmcnt(0)
	v_add_f32_e32 v11, v11, v12
; __device__ __forceinline__ unsigned moba_select(int b, int h, int qb, const f16_t* Q, const float* __restrict__ kms) {
;     ...
;     for (int j = 0; j < 7; ++j) {
;         float s = 0.f;
;         if (j < qb) {
;             const float* km = kms + (size_t)(b * NBLK + j) * AW + h * HD + hi * 8;
; #pragma unroll
;             for (int d0 = 0; d0 < 4; ++d0) {
;                 const f32x4 k0 = *(const f32x4*)(km + d0 * 16), k1 = *(const f32x4*)(km + d0 * 16 + 4);
;                 s += (float)qr[d0][0] * k0[0] + (float)qr[d0][1] * k0[1] + (float)qr[d0][2] * k0[2] + (float)qr[d0][3] * k0[3];
;                 s += (float)qr[d0][4] * k1[0] + (float)qr[d0][5] * k1[1] + (float)qr[d0][6] * k1[2] + (float)qr[d0][7] * k1[3];
;             }
;             s += __shfl_xor(s, 32);
;         } else s = -INFINITY;
;         gsc[j] = s;
.LBB0_533:
	s_cmp_gt_u32 s70, 5
	s_cselect_b64 s[36:37], -1, 0
	s_cmp_lt_u32 s70, 6
	s_cbranch_scc1 .LBB0_535
	v_lshl_add_u64 v[20:21], v[132:133], 0, s[96:97]
	global_load_dwordx4 v[12:15], v[20:21], off
	global_load_dwordx4 v[16:19], v[20:21], off offset:16
	global_load_dwordx4 v[218:221], v[20:21], off offset:64
	global_load_dwordx4 v[222:225], v[20:21], off offset:80
	global_load_dwordx4 v[232:235], v[20:21], off offset:128
	global_load_dwordx4 v[236:239], v[20:21], off offset:144
	global_load_dwordx4 v[240:243], v[20:21], off offset:192
	global_load_dwordx4 v[244:247], v[20:21], off offset:208
	s_waitcnt vmcnt(7)
	v_mov_b32_e32 v22, v12
	s_waitcnt vmcnt(6)
	v_mov_b32_e32 v23, v16
	v_mov_b32_e32 v16, v13
	v_pk_mul_f32 v[12:13], v[16:17], v[138:139]
	v_mov_b32_e32 v16, v14
	v_pk_fma_f32 v[12:13], v[22:23], v[130:131], v[12:13]
	v_mov_b32_e32 v17, v18
	v_pk_fma_f32 v[12:13], v[16:17], v[134:135], v[12:13]
	v_mov_b32_e32 v18, v15
	v_pk_fma_f32 v[12:13], v[18:19], v[136:137], v[12:13]
	s_nop 0
	v_add_f32_e32 v10, 0, v12
	v_add_f32_e32 v10, v10, v13
	s_waitcnt vmcnt(4)
	v_mov_b32_e32 v12, v218
	v_mov_b32_e32 v13, v219
	v_mov_b32_e32 v14, v220
	v_mov_b32_e32 v15, v221
	v_mov_b32_e32 v16, v222
	v_mov_b32_e32 v17, v223
	v_mov_b32_e32 v18, v224
	v_mov_b32_e32 v19, v225
	v_mov_b32_e32 v22, v12
	v_mov_b32_e32 v23, v16
	v_mov_b32_e32 v16, v13
	v_pk_mul_f32 v[12:13], v[16:17], v[128:129]
	v_mov_b32_e32 v16, v14
	v_pk_fma_f32 v[12:13], v[22:23], v[122:123], v[12:13]
	v_mov_b32_e32 v17, v18
	v_pk_fma_f32 v[12:13], v[16:17], v[124:125], v[12:13]
	v_mov_b32_e32 v18, v15
	v_pk_fma_f32 v[12:13], v[18:19], v[126:127], v[12:13]
	s_nop 0
	v_add_f32_e32 v10, v10, v12
	v_add_f32_e32 v10, v10, v13
	s_waitcnt vmcnt(2)
	v_mov_b32_e32 v12, v232
	v_mov_b32_e32 v13, v233
	v_mov_b32_e32 v14, v234
	v_mov_b32_e32 v15, v235
	v_mov_b32_e32 v16, v236
	v_mov_b32_e32 v17, v237
	v_mov_b32_e32 v18, v238
	v_mov_b32_e32 v19, v239
	v_mov_b32_e32 v22, v12
	v_mov_b32_e32 v23, v16
	v_mov_b32_e32 v16, v13
	v_pk_mul_f32 v[12:13], v[16:17], v[120:121]
	v_mov_b32_e32 v16, v14
	v_pk_fma_f32 v[12:13], v[22:23], v[114:115], v[12:13]
	v_mov_b32_e32 v17, v18
	v_pk_fma_f32 v[12:13], v[16:17], v[116:117], v[12:13]
	v_mov_b32_e32 v18, v15
	v_pk_fma_f32 v[12:13], v[18:19], v[118:119], v[12:13]
	s_nop 0
	v_add_f32_e32 v10, v10, v12
	v_add_f32_e32 v10, v10, v13
	s_waitcnt vmcnt(0)
	v_mov_b32_e32 v12, v240
	v_mov_b32_e32 v13, v241
	v_mov_b32_e32 v14, v242
	v_mov_b32_e32 v15, v243
	v_mov_b32_e32 v16, v244
	v_mov_b32_e32 v17, v245
	v_mov_b32_e32 v18, v246
	v_mov_b32_e32 v19, v247
	v_mov_b32_e32 v20, v12
	v_mov_b32_e32 v21, v16
	v_mov_b32_e32 v16, v13
	v_pk_mul_f32 v[12:13], v[16:17], v[112:113]
	v_mov_b32_e32 v16, v14
	v_pk_fma_f32 v[12:13], v[20:21], v[110:111], v[12:13]
	v_mov_b32_e32 v17, v18
	v_pk_fma_f32 v[12:13], v[16:17], v[108:109], v[12:13]
	v_mov_b32_e32 v18, v15
	v_pk_fma_f32 v[12:13], v[18:19], v[106:107], v[12:13]
	s_nop 0
	v_add_f32_e32 v10, v10, v12
	v_add_f32_e32 v10, v10, v13
	ds_bpermute_b32 v12, v151, v10
	s_waitcnt lgkmcnt(0)
	v_add_f32_e32 v10, v10, v12
.LBB0_535:
	s_cmp_eq_u32 s70, 7
	s_cselect_b64 s[30:31], -1, 0
	s_cmp_lg_u32 s70, 7
	v_mov_b32_e32 v12, 0xff800000
	s_cbranch_scc1 .LBB0_537
	v_lshl_add_u64 v[20:21], v[132:133], 0, s[72:73]
	global_load_dwordx4 v[12:15], v[20:21], off
	global_load_dwordx4 v[16:19], v[20:21], off offset:16
	global_load_dwordx4 v[218:221], v[20:21], off offset:64
	global_load_dwordx4 v[222:225], v[20:21], off offset:80
	global_load_dwordx4 v[232:235], v[20:21], off offset:128
	global_load_dwordx4 v[236:239], v[20:21], off offset:144
	global_load_dwordx4 v[240:243], v[20:21], off offset:192
	global_load_dwordx4 v[244:247], v[20:21], off offset:208
	s_waitcnt vmcnt(7)
	v_mov_b32_e32 v22, v12
	s_waitcnt vmcnt(6)
	v_mov_b32_e32 v23, v16
	v_mov_b32_e32 v16, v13
	v_pk_mul_f32 v[12:13], v[16:17], v[138:139]
	v_mov_b32_e32 v16, v14
	v_pk_fma_f32 v[12:13], v[22:23], v[130:131], v[12:13]
	v_mov_b32_e32 v17, v18
	v_pk_fma_f32 v[12:13], v[16:17], v[134:135], v[12:13]
	v_mov_b32_e32 v18, v15
	v_pk_fma_f32 v[12:13], v[18:19], v[136:137], v[12:13]
	s_nop 0
	v_add_f32_e32 v12, 0, v12
	v_add_f32_e32 v24, v12, v13
	s_waitcnt vmcnt(4)
	v_mov_b32_e32 v12, v218
	v_mov_b32_e32 v13, v219
	v_mov_b32_e32 v14, v220
	v_mov_b32_e32 v15, v221
	v_mov_b32_e32 v16, v222
	v_mov_b32_e32 v17, v223
	v_mov_b32_e32 v18, v224
	v_mov_b32_e32 v19, v225
	v_mov_b32_e32 v22, v12
	v_mov_b32_e32 v23, v16
	v_mov_b32_e32 v16, v13
	v_pk_mul_f32 v[12:13], v[16:17], v[128:129]
	v_mov_b32_e32 v16, v14
	v_pk_fma_f32 v[12:13], v[22:23], v[122:123], v[12:13]
	v_mov_b32_e32 v17, v18
	v_pk_fma_f32 v[12:13], v[16:17], v[124:125], v[12:13]
	v_mov_b32_e32 v18, v15
	v_pk_fma_f32 v[12:13], v[18:19], v[126:127], v[12:13]
	s_nop 0
	v_add_f32_e32 v12, v24, v12
	v_add_f32_e32 v24, v12, v13
	s_waitcnt vmcnt(2)
	v_mov_b32_e32 v12, v232
	v_mov_b32_e32 v13, v233
	v_mov_b32_e32 v14, v234
	v_mov_b32_e32 v15, v235
	v_mov_b32_e32 v16, v236
	v_mov_b32_e32 v17, v237
	v_mov_b32_e32 v18, v238
	v_mov_b32_e32 v19, v239
	v_mov_b32_e32 v22, v12
	v_mov_b32_e32 v23, v16
	v_mov_b32_e32 v16, v13
	v_pk_mul_f32 v[12:13], v[16:17], v[120:121]
	v_mov_b32_e32 v16, v14
	v_pk_fma_f32 v[12:13], v[22:23], v[114:115], v[12:13]
	v_mov_b32_e32 v17, v18
	v_pk_fma_f32 v[12:13], v[16:17], v[116:117], v[12:13]
	v_mov_b32_e32 v18, v15
	v_pk_fma_f32 v[12:13], v[18:19], v[118:119], v[12:13]
	s_nop 0
	v_add_f32_e32 v12, v24, v12
	v_add_f32_e32 v22, v12, v13
	s_waitcnt vmcnt(0)
	v_mov_b32_e32 v12, v240
	v_mov_b32_e32 v13, v241
	v_mov_b32_e32 v14, v242
	v_mov_b32_e32 v15, v243
	v_mov_b32_e32 v16, v244
	v_mov_b32_e32 v17, v245
	v_mov_b32_e32 v18, v246
	v_mov_b32_e32 v19, v247
	v_mov_b32_e32 v20, v12
	v_mov_b32_e32 v21, v16
	v_mov_b32_e32 v16, v13
	v_pk_mul_f32 v[12:13], v[16:17], v[112:113]
	v_mov_b32_e32 v16, v14
	v_pk_fma_f32 v[12:13], v[20:21], v[110:111], v[12:13]
	v_mov_b32_e32 v17, v18
	v_pk_fma_f32 v[12:13], v[16:17], v[108:109], v[12:13]
	v_mov_b32_e32 v18, v15
	v_pk_fma_f32 v[12:13], v[18:19], v[106:107], v[12:13]
	s_nop 0
	v_add_f32_e32 v12, v22, v12
	v_add_f32_e32 v12, v12, v13
	ds_bpermute_b32 v13, v151, v12
	s_waitcnt lgkmcnt(0)
	v_add_f32_e32 v12, v12, v13
